# retention-output unit epilogue rewritten (DPP/permlane16 batched reductions); gMLP epilogue still the compiler's
# baseline (speedup 1.0000x reference)
; #define LAS __attribute__((address_space(3)))
; __device__ __forceinline__ float bf2f(unsigned h) { return __uint_as_float(h << 16); }
; __device__ __forceinline__ unsigned cvt_pk_bf16(float lo, float hi) { unsigned r; asm volatile("v_cvt_pk_bf16_f32 %0, %1, %2" : "=v"(r) : "v"(lo), "v"(hi)); return r; }
; __device__ __forceinline__ int crow(int r, int hi) { return (r & 3) + 8 * (r >> 2) + 4 * hi; }
; __device__ __forceinline__ void retout_phase(const bf16_t* RQ, const bf16_t* RK, const bf16_t* RV, const bf16_t* RG, const bf16_t* ST, bf16_t* Y, lptr lds, int blk, int G, int tid_) {
;     ...
;         const LAS bf16_t* gp = (const LAS bf16_t*)(lds + ci * 32768 + 16384 + (32 * tb) * 256) + r32; bf16_t* yp = Y + ((size_t)(b * SEQ + n * 64 + 32 * tb)) * DM + 1024 + hr * HD + r32;
; #pragma unroll
;         for (int r = 0; r < 16; ++r) { const int tr = crow(r, hi);
;             float v0 = o[0][r], v1 = o[1][r], v2 = o[2][r], v3 = o[3][r];
;             float ss = (v0 * v0 + v1 * v1) + (v2 * v2 + v3 * v3);
;             ss += __shfl_xor(ss, 1); ss += __shfl_xor(ss, 2); ss += __shfl_xor(ss, 4); ss += __shfl_xor(ss, 8); ss += __shfl_xor(ss, 16);
;             const float rs = rsqrtf(ss * (1.0f / 128.0f) + EPS);
;             v0 *= rs * bf2f(gp[tr * HD]); v1 *= rs * bf2f(gp[tr * HD + 32]); v2 *= rs * bf2f(gp[tr * HD + 64]); v3 *= rs * bf2f(gp[tr * HD + 96]);
;             const float n0 = __shfl_xor(v0, 1), n1 = __shfl_xor(v1, 1), n2 = __shfl_xor(v2, 1), n3 = __shfl_xor(v3, 1);
;             if ((r32 & 1) == 0) { bf16_t* op = yp + (size_t)tr * DM;
;                 *(unsigned*)(op) = cvt_pk_bf16(v0, n0); *(unsigned*)(op + 32) = cvt_pk_bf16(v1, n1); *(unsigned*)(op + 64) = cvt_pk_bf16(v2, n2); *(unsigned*)(op + 96) = cvt_pk_bf16(v3, n3); } }
.LBB0_788:
	s_lshl_b32 s4, s26, 13
	s_add_i32 s27, s27, s4
	s_and_b32 s4, s20, 0xfffff000
	s_add_i32 s25, s25, s4
	s_or_b32 s4, s25, s28
	s_ashr_i32 s5, s4, 31
	s_lshl_b64 s[4:5], s[4:5], 12
	s_add_u32 s4, s16, s4
	s_addc_u32 s5, s17, s5
	s_lshl_b32 s12, s24, 8
	s_add_u32 s4, s4, s12
	s_addc_u32 s5, s5, 0
	s_add_u32 s4, s4, 0x39800800
	s_addc_u32 s5, s5, 0
	v_lshlrev_b32_e32 v162, 1, v123
	v_cmp_eq_u32_e32 vcc, 0, v122
	v_add_u32_e32 v78, s27, v162
	v_lshl_add_u32 v78, v124, 10, v78
	v_lshl_add_u32 v162, v124, 14, v162
	v_pk_mul_f32 v[66:67], v[2:3], v[2:3]
	v_pk_mul_f32 v[68:69], v[4:5], v[4:5]
	v_pk_fma_f32 v[66:67], v[18:19], v[18:19], v[66:67]
	v_pk_fma_f32 v[68:69], v[20:21], v[20:21], v[68:69]
	v_pk_fma_f32 v[66:67], v[34:35], v[34:35], v[66:67]
	v_pk_fma_f32 v[68:69], v[36:37], v[36:37], v[68:69]
	v_pk_fma_f32 v[66:67], v[50:51], v[50:51], v[66:67]
	v_pk_fma_f32 v[68:69], v[52:53], v[52:53], v[68:69]
	s_nop 1
	v_add_f32_dpp v66, v66, v66 quad_perm:[1,0,3,2] row_mask:0xf bank_mask:0xf
	v_add_f32_dpp v67, v67, v67 quad_perm:[1,0,3,2] row_mask:0xf bank_mask:0xf
	v_add_f32_dpp v68, v68, v68 quad_perm:[1,0,3,2] row_mask:0xf bank_mask:0xf
	v_add_f32_dpp v69, v69, v69 quad_perm:[1,0,3,2] row_mask:0xf bank_mask:0xf
	v_add_f32_dpp v66, v66, v66 quad_perm:[2,3,0,1] row_mask:0xf bank_mask:0xf
	v_add_f32_dpp v67, v67, v67 quad_perm:[2,3,0,1] row_mask:0xf bank_mask:0xf
	v_add_f32_dpp v68, v68, v68 quad_perm:[2,3,0,1] row_mask:0xf bank_mask:0xf
	v_add_f32_dpp v69, v69, v69 quad_perm:[2,3,0,1] row_mask:0xf bank_mask:0xf
	v_add_f32_dpp v66, v66, v66 row_half_mirror row_mask:0xf bank_mask:0xf
	v_add_f32_dpp v67, v67, v67 row_half_mirror row_mask:0xf bank_mask:0xf
	v_add_f32_dpp v68, v68, v68 row_half_mirror row_mask:0xf bank_mask:0xf
	v_add_f32_dpp v69, v69, v69 row_half_mirror row_mask:0xf bank_mask:0xf
	v_add_f32_dpp v66, v66, v66 row_mirror row_mask:0xf bank_mask:0xf
	v_add_f32_dpp v67, v67, v67 row_mirror row_mask:0xf bank_mask:0xf
	v_add_f32_dpp v68, v68, v68 row_mirror row_mask:0xf bank_mask:0xf
	v_add_f32_dpp v69, v69, v69 row_mirror row_mask:0xf bank_mask:0xf
	v_mov_b32_e32 v70, v66
	v_mov_b32_e32 v71, v67
	v_mov_b32_e32 v72, v68
	v_mov_b32_e32 v73, v69
	v_permlane16_swap_b32_e32 v66, v70
	v_permlane16_swap_b32_e32 v67, v71
	v_permlane16_swap_b32_e32 v68, v72
	v_permlane16_swap_b32_e32 v69, v73
	v_add_f32_e32 v66, v66, v70
	v_add_f32_e32 v67, v67, v71
	v_add_f32_e32 v68, v68, v72
	v_add_f32_e32 v69, v69, v73
	v_fmamk_f32 v66, v66, 0x3c000000, v192
	v_fmamk_f32 v67, v67, 0x3c000000, v192
	v_fmamk_f32 v68, v68, 0x3c000000, v192
	v_fmamk_f32 v69, v69, 0x3c000000, v192
	v_rsq_f32_e32 v66, v66
	v_rsq_f32_e32 v67, v67
	v_rsq_f32_e32 v68, v68
	v_rsq_f32_e32 v69, v69
	ds_read_u16 v74, v78 offset:16384
	ds_read_u16 v75, v78 offset:16448
	ds_read_u16 v76, v78 offset:16512
	ds_read_u16 v77, v78 offset:16576
	s_waitcnt lgkmcnt(0)
	v_lshlrev_b32_e32 v74, 16, v74
	v_lshlrev_b32_e32 v75, 16, v75
	v_lshlrev_b32_e32 v76, 16, v76
	v_lshlrev_b32_e32 v77, 16, v77
	v_mul_f32_e32 v74, v66, v74
	v_mul_f32_e32 v75, v66, v75
	v_mul_f32_e32 v76, v66, v76
	v_mul_f32_e32 v77, v66, v77
	v_mul_f32_e32 v2, v2, v74
	v_mul_f32_e32 v18, v18, v75
	v_mul_f32_e32 v34, v34, v76
	v_mul_f32_e32 v50, v50, v77
	s_nop 0
	v_mov_b32_dpp v70, v2 quad_perm:[1,0,3,2] row_mask:0xf bank_mask:0xf
	v_mov_b32_dpp v71, v18 quad_perm:[1,0,3,2] row_mask:0xf bank_mask:0xf
	v_mov_b32_dpp v72, v34 quad_perm:[1,0,3,2] row_mask:0xf bank_mask:0xf
	v_mov_b32_dpp v73, v50 quad_perm:[1,0,3,2] row_mask:0xf bank_mask:0xf
	v_cvt_pk_bf16_f32 v2, v2, v70
	v_cvt_pk_bf16_f32 v18, v18, v71
	v_cvt_pk_bf16_f32 v34, v34, v72
	v_cvt_pk_bf16_f32 v50, v50, v73
	ds_read_u16 v74, v78 offset:16640
	ds_read_u16 v75, v78 offset:16704
	ds_read_u16 v76, v78 offset:16768
	ds_read_u16 v77, v78 offset:16832
	s_waitcnt lgkmcnt(0)
	v_lshlrev_b32_e32 v74, 16, v74
	v_lshlrev_b32_e32 v75, 16, v75
	v_lshlrev_b32_e32 v76, 16, v76
	v_lshlrev_b32_e32 v77, 16, v77
	v_mul_f32_e32 v74, v67, v74
	v_mul_f32_e32 v75, v67, v75
	v_mul_f32_e32 v76, v67, v76
	v_mul_f32_e32 v77, v67, v77
	v_mul_f32_e32 v3, v3, v74
	v_mul_f32_e32 v19, v19, v75
	v_mul_f32_e32 v35, v35, v76
	v_mul_f32_e32 v51, v51, v77
	s_nop 0
	v_mov_b32_dpp v70, v3 quad_perm:[1,0,3,2] row_mask:0xf bank_mask:0xf
	v_mov_b32_dpp v71, v19 quad_perm:[1,0,3,2] row_mask:0xf bank_mask:0xf
	v_mov_b32_dpp v72, v35 quad_perm:[1,0,3,2] row_mask:0xf bank_mask:0xf
	v_mov_b32_dpp v73, v51 quad_perm:[1,0,3,2] row_mask:0xf bank_mask:0xf
	v_cvt_pk_bf16_f32 v3, v3, v70
	v_cvt_pk_bf16_f32 v19, v19, v71
	v_cvt_pk_bf16_f32 v35, v35, v72
	v_cvt_pk_bf16_f32 v51, v51, v73
	ds_read_u16 v74, v78 offset:16896
	ds_read_u16 v75, v78 offset:16960
	ds_read_u16 v76, v78 offset:17024
	ds_read_u16 v77, v78 offset:17088
	s_waitcnt lgkmcnt(0)
	v_lshlrev_b32_e32 v74, 16, v74
	v_lshlrev_b32_e32 v75, 16, v75
	v_lshlrev_b32_e32 v76, 16, v76
	v_lshlrev_b32_e32 v77, 16, v77
	v_mul_f32_e32 v74, v68, v74
	v_mul_f32_e32 v75, v68, v75
	v_mul_f32_e32 v76, v68, v76
	v_mul_f32_e32 v77, v68, v77
	v_mul_f32_e32 v4, v4, v74
	v_mul_f32_e32 v20, v20, v75
	v_mul_f32_e32 v36, v36, v76
	v_mul_f32_e32 v52, v52, v77
	s_nop 0
	v_mov_b32_dpp v70, v4 quad_perm:[1,0,3,2] row_mask:0xf bank_mask:0xf
	v_mov_b32_dpp v71, v20 quad_perm:[1,0,3,2] row_mask:0xf bank_mask:0xf
	v_mov_b32_dpp v72, v36 quad_perm:[1,0,3,2] row_mask:0xf bank_mask:0xf
	v_mov_b32_dpp v73, v52 quad_perm:[1,0,3,2] row_mask:0xf bank_mask:0xf
	v_cvt_pk_bf16_f32 v4, v4, v70
	v_cvt_pk_bf16_f32 v20, v20, v71
	v_cvt_pk_bf16_f32 v36, v36, v72
	v_cvt_pk_bf16_f32 v52, v52, v73
	ds_read_u16 v74, v78 offset:17152
	ds_read_u16 v75, v78 offset:17216
	ds_read_u16 v76, v78 offset:17280
	ds_read_u16 v77, v78 offset:17344
	s_waitcnt lgkmcnt(0)
; #define LAS __attribute__((address_space(3)))
; __device__ __forceinline__ float bf2f(unsigned h) { return __uint_as_float(h << 16); }
; __device__ __forceinline__ unsigned cvt_pk_bf16(float lo, float hi) { unsigned r; asm volatile("v_cvt_pk_bf16_f32 %0, %1, %2" : "=v"(r) : "v"(lo), "v"(hi)); return r; }
; __device__ __forceinline__ int crow(int r, int hi) { return (r & 3) + 8 * (r >> 2) + 4 * hi; }
; __device__ __forceinline__ void retout_phase(const bf16_t* RQ, const bf16_t* RK, const bf16_t* RV, const bf16_t* RG, const bf16_t* ST, bf16_t* Y, lptr lds, int blk, int G, int tid_) {
;     ...
;         const LAS bf16_t* gp = (const LAS bf16_t*)(lds + ci * 32768 + 16384 + (32 * tb) * 256) + r32; bf16_t* yp = Y + ((size_t)(b * SEQ + n * 64 + 32 * tb)) * DM + 1024 + hr * HD + r32;
; #pragma unroll
;         for (int r = 0; r < 16; ++r) { const int tr = crow(r, hi);
;             float v0 = o[0][r], v1 = o[1][r], v2 = o[2][r], v3 = o[3][r];
;             float ss = (v0 * v0 + v1 * v1) + (v2 * v2 + v3 * v3);
;             ss += __shfl_xor(ss, 1); ss += __shfl_xor(ss, 2); ss += __shfl_xor(ss, 4); ss += __shfl_xor(ss, 8); ss += __shfl_xor(ss, 16);
;             const float rs = rsqrtf(ss * (1.0f / 128.0f) + EPS);
;             v0 *= rs * bf2f(gp[tr * HD]); v1 *= rs * bf2f(gp[tr * HD + 32]); v2 *= rs * bf2f(gp[tr * HD + 64]); v3 *= rs * bf2f(gp[tr * HD + 96]);
;             const float n0 = __shfl_xor(v0, 1), n1 = __shfl_xor(v1, 1), n2 = __shfl_xor(v2, 1), n3 = __shfl_xor(v3, 1);
;             if ((r32 & 1) == 0) { bf16_t* op = yp + (size_t)tr * DM;
;                 *(unsigned*)(op) = cvt_pk_bf16(v0, n0); *(unsigned*)(op + 32) = cvt_pk_bf16(v1, n1); *(unsigned*)(op + 64) = cvt_pk_bf16(v2, n2); *(unsigned*)(op + 96) = cvt_pk_bf16(v3, n3); } }
	v_lshlrev_b32_e32 v74, 16, v74
	v_lshlrev_b32_e32 v75, 16, v75
	v_lshlrev_b32_e32 v76, 16, v76
	v_lshlrev_b32_e32 v77, 16, v77
	v_mul_f32_e32 v74, v69, v74
	v_mul_f32_e32 v75, v69, v75
	v_mul_f32_e32 v76, v69, v76
	v_mul_f32_e32 v77, v69, v77
	v_mul_f32_e32 v5, v5, v74
	v_mul_f32_e32 v21, v21, v75
	v_mul_f32_e32 v37, v37, v76
	v_mul_f32_e32 v53, v53, v77
	s_nop 0
	v_mov_b32_dpp v70, v5 quad_perm:[1,0,3,2] row_mask:0xf bank_mask:0xf
	v_mov_b32_dpp v71, v21 quad_perm:[1,0,3,2] row_mask:0xf bank_mask:0xf
	v_mov_b32_dpp v72, v37 quad_perm:[1,0,3,2] row_mask:0xf bank_mask:0xf
	v_mov_b32_dpp v73, v53 quad_perm:[1,0,3,2] row_mask:0xf bank_mask:0xf
	v_cvt_pk_bf16_f32 v5, v5, v70
	v_cvt_pk_bf16_f32 v21, v21, v71
	v_cvt_pk_bf16_f32 v37, v37, v72
	v_cvt_pk_bf16_f32 v53, v53, v73
	v_pk_mul_f32 v[66:67], v[6:7], v[6:7]
	v_pk_mul_f32 v[68:69], v[8:9], v[8:9]
	v_pk_fma_f32 v[66:67], v[22:23], v[22:23], v[66:67]
	v_pk_fma_f32 v[68:69], v[24:25], v[24:25], v[68:69]
	v_pk_fma_f32 v[66:67], v[38:39], v[38:39], v[66:67]
	v_pk_fma_f32 v[68:69], v[40:41], v[40:41], v[68:69]
	v_pk_fma_f32 v[66:67], v[54:55], v[54:55], v[66:67]
	v_pk_fma_f32 v[68:69], v[56:57], v[56:57], v[68:69]
	s_nop 1
	v_add_f32_dpp v66, v66, v66 quad_perm:[1,0,3,2] row_mask:0xf bank_mask:0xf
	v_add_f32_dpp v67, v67, v67 quad_perm:[1,0,3,2] row_mask:0xf bank_mask:0xf
	v_add_f32_dpp v68, v68, v68 quad_perm:[1,0,3,2] row_mask:0xf bank_mask:0xf
	v_add_f32_dpp v69, v69, v69 quad_perm:[1,0,3,2] row_mask:0xf bank_mask:0xf
	v_add_f32_dpp v66, v66, v66 quad_perm:[2,3,0,1] row_mask:0xf bank_mask:0xf
	v_add_f32_dpp v67, v67, v67 quad_perm:[2,3,0,1] row_mask:0xf bank_mask:0xf
	v_add_f32_dpp v68, v68, v68 quad_perm:[2,3,0,1] row_mask:0xf bank_mask:0xf
	v_add_f32_dpp v69, v69, v69 quad_perm:[2,3,0,1] row_mask:0xf bank_mask:0xf
	v_add_f32_dpp v66, v66, v66 row_half_mirror row_mask:0xf bank_mask:0xf
	v_add_f32_dpp v67, v67, v67 row_half_mirror row_mask:0xf bank_mask:0xf
	v_add_f32_dpp v68, v68, v68 row_half_mirror row_mask:0xf bank_mask:0xf
	v_add_f32_dpp v69, v69, v69 row_half_mirror row_mask:0xf bank_mask:0xf
	v_add_f32_dpp v66, v66, v66 row_mirror row_mask:0xf bank_mask:0xf
	v_add_f32_dpp v67, v67, v67 row_mirror row_mask:0xf bank_mask:0xf
	v_add_f32_dpp v68, v68, v68 row_mirror row_mask:0xf bank_mask:0xf
	v_add_f32_dpp v69, v69, v69 row_mirror row_mask:0xf bank_mask:0xf
	v_mov_b32_e32 v70, v66
	v_mov_b32_e32 v71, v67
	v_mov_b32_e32 v72, v68
	v_mov_b32_e32 v73, v69
	v_permlane16_swap_b32_e32 v66, v70
	v_permlane16_swap_b32_e32 v67, v71
	v_permlane16_swap_b32_e32 v68, v72
	v_permlane16_swap_b32_e32 v69, v73
	v_add_f32_e32 v66, v66, v70
	v_add_f32_e32 v67, v67, v71
	v_add_f32_e32 v68, v68, v72
	v_add_f32_e32 v69, v69, v73
	v_fmamk_f32 v66, v66, 0x3c000000, v192
	v_fmamk_f32 v67, v67, 0x3c000000, v192
	v_fmamk_f32 v68, v68, 0x3c000000, v192
	v_fmamk_f32 v69, v69, 0x3c000000, v192
	v_rsq_f32_e32 v66, v66
	v_rsq_f32_e32 v67, v67
	v_rsq_f32_e32 v68, v68
	v_rsq_f32_e32 v69, v69
	ds_read_u16 v74, v78 offset:18432
	ds_read_u16 v75, v78 offset:18496
	ds_read_u16 v76, v78 offset:18560
	ds_read_u16 v77, v78 offset:18624
	s_waitcnt lgkmcnt(0)
	v_lshlrev_b32_e32 v74, 16, v74
	v_lshlrev_b32_e32 v75, 16, v75
	v_lshlrev_b32_e32 v76, 16, v76
	v_lshlrev_b32_e32 v77, 16, v77
	v_mul_f32_e32 v74, v66, v74
	v_mul_f32_e32 v75, v66, v75
	v_mul_f32_e32 v76, v66, v76
	v_mul_f32_e32 v77, v66, v77
	v_mul_f32_e32 v6, v6, v74
	v_mul_f32_e32 v22, v22, v75
	v_mul_f32_e32 v38, v38, v76
	v_mul_f32_e32 v54, v54, v77
	s_nop 0
	v_mov_b32_dpp v70, v6 quad_perm:[1,0,3,2] row_mask:0xf bank_mask:0xf
	v_mov_b32_dpp v71, v22 quad_perm:[1,0,3,2] row_mask:0xf bank_mask:0xf
	v_mov_b32_dpp v72, v38 quad_perm:[1,0,3,2] row_mask:0xf bank_mask:0xf
	v_mov_b32_dpp v73, v54 quad_perm:[1,0,3,2] row_mask:0xf bank_mask:0xf
	v_cvt_pk_bf16_f32 v6, v6, v70
	v_cvt_pk_bf16_f32 v22, v22, v71
	v_cvt_pk_bf16_f32 v38, v38, v72
	v_cvt_pk_bf16_f32 v54, v54, v73
	ds_read_u16 v74, v78 offset:18688
	ds_read_u16 v75, v78 offset:18752
	ds_read_u16 v76, v78 offset:18816
	ds_read_u16 v77, v78 offset:18880
	s_waitcnt lgkmcnt(0)
	v_lshlrev_b32_e32 v74, 16, v74
	v_lshlrev_b32_e32 v75, 16, v75
	v_lshlrev_b32_e32 v76, 16, v76
	v_lshlrev_b32_e32 v77, 16, v77
	v_mul_f32_e32 v74, v67, v74
	v_mul_f32_e32 v75, v67, v75
	v_mul_f32_e32 v76, v67, v76
	v_mul_f32_e32 v77, v67, v77
	v_mul_f32_e32 v7, v7, v74
	v_mul_f32_e32 v23, v23, v75
	v_mul_f32_e32 v39, v39, v76
	v_mul_f32_e32 v55, v55, v77
	s_nop 0
	v_mov_b32_dpp v70, v7 quad_perm:[1,0,3,2] row_mask:0xf bank_mask:0xf
	v_mov_b32_dpp v71, v23 quad_perm:[1,0,3,2] row_mask:0xf bank_mask:0xf
	v_mov_b32_dpp v72, v39 quad_perm:[1,0,3,2] row_mask:0xf bank_mask:0xf
	v_mov_b32_dpp v73, v55 quad_perm:[1,0,3,2] row_mask:0xf bank_mask:0xf
	v_cvt_pk_bf16_f32 v7, v7, v70
	v_cvt_pk_bf16_f32 v23, v23, v71
	v_cvt_pk_bf16_f32 v39, v39, v72
	v_cvt_pk_bf16_f32 v55, v55, v73
	ds_read_u16 v74, v78 offset:18944
	ds_read_u16 v75, v78 offset:19008
	ds_read_u16 v76, v78 offset:19072
	ds_read_u16 v77, v78 offset:19136
	s_waitcnt lgkmcnt(0)
	v_lshlrev_b32_e32 v74, 16, v74
	v_lshlrev_b32_e32 v75, 16, v75
	v_lshlrev_b32_e32 v76, 16, v76
	v_lshlrev_b32_e32 v77, 16, v77
	v_mul_f32_e32 v74, v68, v74
	v_mul_f32_e32 v75, v68, v75
	v_mul_f32_e32 v76, v68, v76
	v_mul_f32_e32 v77, v68, v77
	v_mul_f32_e32 v8, v8, v74
	v_mul_f32_e32 v24, v24, v75
	v_mul_f32_e32 v40, v40, v76
	v_mul_f32_e32 v56, v56, v77
	s_nop 0
	v_mov_b32_dpp v70, v8 quad_perm:[1,0,3,2] row_mask:0xf bank_mask:0xf
	v_mov_b32_dpp v71, v24 quad_perm:[1,0,3,2] row_mask:0xf bank_mask:0xf
	v_mov_b32_dpp v72, v40 quad_perm:[1,0,3,2] row_mask:0xf bank_mask:0xf
	v_mov_b32_dpp v73, v56 quad_perm:[1,0,3,2] row_mask:0xf bank_mask:0xf
	v_cvt_pk_bf16_f32 v8, v8, v70
	v_cvt_pk_bf16_f32 v24, v24, v71
	v_cvt_pk_bf16_f32 v40, v40, v72
	v_cvt_pk_bf16_f32 v56, v56, v73
	ds_read_u16 v74, v78 offset:19200
	ds_read_u16 v75, v78 offset:19264
	ds_read_u16 v76, v78 offset:19328
	ds_read_u16 v77, v78 offset:19392
	s_waitcnt lgkmcnt(0)
; #define LAS __attribute__((address_space(3)))
; __device__ __forceinline__ float bf2f(unsigned h) { return __uint_as_float(h << 16); }
; __device__ __forceinline__ unsigned cvt_pk_bf16(float lo, float hi) { unsigned r; asm volatile("v_cvt_pk_bf16_f32 %0, %1, %2" : "=v"(r) : "v"(lo), "v"(hi)); return r; }
; __device__ __forceinline__ int crow(int r, int hi) { return (r & 3) + 8 * (r >> 2) + 4 * hi; }
; __device__ __forceinline__ void retout_phase(const bf16_t* RQ, const bf16_t* RK, const bf16_t* RV, const bf16_t* RG, const bf16_t* ST, bf16_t* Y, lptr lds, int blk, int G, int tid_) {
;     ...
;         const LAS bf16_t* gp = (const LAS bf16_t*)(lds + ci * 32768 + 16384 + (32 * tb) * 256) + r32; bf16_t* yp = Y + ((size_t)(b * SEQ + n * 64 + 32 * tb)) * DM + 1024 + hr * HD + r32;
; #pragma unroll
;         for (int r = 0; r < 16; ++r) { const int tr = crow(r, hi);
;             float v0 = o[0][r], v1 = o[1][r], v2 = o[2][r], v3 = o[3][r];
;             float ss = (v0 * v0 + v1 * v1) + (v2 * v2 + v3 * v3);
;             ss += __shfl_xor(ss, 1); ss += __shfl_xor(ss, 2); ss += __shfl_xor(ss, 4); ss += __shfl_xor(ss, 8); ss += __shfl_xor(ss, 16);
;             const float rs = rsqrtf(ss * (1.0f / 128.0f) + EPS);
;             v0 *= rs * bf2f(gp[tr * HD]); v1 *= rs * bf2f(gp[tr * HD + 32]); v2 *= rs * bf2f(gp[tr * HD + 64]); v3 *= rs * bf2f(gp[tr * HD + 96]);
;             const float n0 = __shfl_xor(v0, 1), n1 = __shfl_xor(v1, 1), n2 = __shfl_xor(v2, 1), n3 = __shfl_xor(v3, 1);
;             if ((r32 & 1) == 0) { bf16_t* op = yp + (size_t)tr * DM;
;                 *(unsigned*)(op) = cvt_pk_bf16(v0, n0); *(unsigned*)(op + 32) = cvt_pk_bf16(v1, n1); *(unsigned*)(op + 64) = cvt_pk_bf16(v2, n2); *(unsigned*)(op + 96) = cvt_pk_bf16(v3, n3); } }
	v_lshlrev_b32_e32 v74, 16, v74
	v_lshlrev_b32_e32 v75, 16, v75
	v_lshlrev_b32_e32 v76, 16, v76
	v_lshlrev_b32_e32 v77, 16, v77
	v_mul_f32_e32 v74, v69, v74
	v_mul_f32_e32 v75, v69, v75
	v_mul_f32_e32 v76, v69, v76
	v_mul_f32_e32 v77, v69, v77
	v_mul_f32_e32 v9, v9, v74
	v_mul_f32_e32 v25, v25, v75
	v_mul_f32_e32 v41, v41, v76
	v_mul_f32_e32 v57, v57, v77
	s_nop 0
	v_mov_b32_dpp v70, v9 quad_perm:[1,0,3,2] row_mask:0xf bank_mask:0xf
	v_mov_b32_dpp v71, v25 quad_perm:[1,0,3,2] row_mask:0xf bank_mask:0xf
	v_mov_b32_dpp v72, v41 quad_perm:[1,0,3,2] row_mask:0xf bank_mask:0xf
	v_mov_b32_dpp v73, v57 quad_perm:[1,0,3,2] row_mask:0xf bank_mask:0xf
	v_cvt_pk_bf16_f32 v9, v9, v70
	v_cvt_pk_bf16_f32 v25, v25, v71
	v_cvt_pk_bf16_f32 v41, v41, v72
	v_cvt_pk_bf16_f32 v57, v57, v73
	v_pk_mul_f32 v[66:67], v[10:11], v[10:11]
	v_pk_mul_f32 v[68:69], v[12:13], v[12:13]
	v_pk_fma_f32 v[66:67], v[26:27], v[26:27], v[66:67]
	v_pk_fma_f32 v[68:69], v[28:29], v[28:29], v[68:69]
	v_pk_fma_f32 v[66:67], v[42:43], v[42:43], v[66:67]
	v_pk_fma_f32 v[68:69], v[44:45], v[44:45], v[68:69]
	v_pk_fma_f32 v[66:67], v[58:59], v[58:59], v[66:67]
	v_pk_fma_f32 v[68:69], v[60:61], v[60:61], v[68:69]
	s_nop 1
	v_add_f32_dpp v66, v66, v66 quad_perm:[1,0,3,2] row_mask:0xf bank_mask:0xf
	v_add_f32_dpp v67, v67, v67 quad_perm:[1,0,3,2] row_mask:0xf bank_mask:0xf
	v_add_f32_dpp v68, v68, v68 quad_perm:[1,0,3,2] row_mask:0xf bank_mask:0xf
	v_add_f32_dpp v69, v69, v69 quad_perm:[1,0,3,2] row_mask:0xf bank_mask:0xf
	v_add_f32_dpp v66, v66, v66 quad_perm:[2,3,0,1] row_mask:0xf bank_mask:0xf
	v_add_f32_dpp v67, v67, v67 quad_perm:[2,3,0,1] row_mask:0xf bank_mask:0xf
	v_add_f32_dpp v68, v68, v68 quad_perm:[2,3,0,1] row_mask:0xf bank_mask:0xf
	v_add_f32_dpp v69, v69, v69 quad_perm:[2,3,0,1] row_mask:0xf bank_mask:0xf
	v_add_f32_dpp v66, v66, v66 row_half_mirror row_mask:0xf bank_mask:0xf
	v_add_f32_dpp v67, v67, v67 row_half_mirror row_mask:0xf bank_mask:0xf
	v_add_f32_dpp v68, v68, v68 row_half_mirror row_mask:0xf bank_mask:0xf
	v_add_f32_dpp v69, v69, v69 row_half_mirror row_mask:0xf bank_mask:0xf
	v_add_f32_dpp v66, v66, v66 row_mirror row_mask:0xf bank_mask:0xf
	v_add_f32_dpp v67, v67, v67 row_mirror row_mask:0xf bank_mask:0xf
	v_add_f32_dpp v68, v68, v68 row_mirror row_mask:0xf bank_mask:0xf
	v_add_f32_dpp v69, v69, v69 row_mirror row_mask:0xf bank_mask:0xf
	v_mov_b32_e32 v70, v66
	v_mov_b32_e32 v71, v67
	v_mov_b32_e32 v72, v68
	v_mov_b32_e32 v73, v69
	v_permlane16_swap_b32_e32 v66, v70
	v_permlane16_swap_b32_e32 v67, v71
	v_permlane16_swap_b32_e32 v68, v72
	v_permlane16_swap_b32_e32 v69, v73
	v_add_f32_e32 v66, v66, v70
	v_add_f32_e32 v67, v67, v71
	v_add_f32_e32 v68, v68, v72
	v_add_f32_e32 v69, v69, v73
	v_fmamk_f32 v66, v66, 0x3c000000, v192
	v_fmamk_f32 v67, v67, 0x3c000000, v192
	v_fmamk_f32 v68, v68, 0x3c000000, v192
	v_fmamk_f32 v69, v69, 0x3c000000, v192
	v_rsq_f32_e32 v66, v66
	v_rsq_f32_e32 v67, v67
	v_rsq_f32_e32 v68, v68
	v_rsq_f32_e32 v69, v69
	ds_read_u16 v74, v78 offset:20480
	ds_read_u16 v75, v78 offset:20544
	ds_read_u16 v76, v78 offset:20608
	ds_read_u16 v77, v78 offset:20672
	s_waitcnt lgkmcnt(0)
	v_lshlrev_b32_e32 v74, 16, v74
	v_lshlrev_b32_e32 v75, 16, v75
	v_lshlrev_b32_e32 v76, 16, v76
	v_lshlrev_b32_e32 v77, 16, v77
	v_mul_f32_e32 v74, v66, v74
	v_mul_f32_e32 v75, v66, v75
	v_mul_f32_e32 v76, v66, v76
	v_mul_f32_e32 v77, v66, v77
	v_mul_f32_e32 v10, v10, v74
	v_mul_f32_e32 v26, v26, v75
	v_mul_f32_e32 v42, v42, v76
	v_mul_f32_e32 v58, v58, v77
	s_nop 0
	v_mov_b32_dpp v70, v10 quad_perm:[1,0,3,2] row_mask:0xf bank_mask:0xf
	v_mov_b32_dpp v71, v26 quad_perm:[1,0,3,2] row_mask:0xf bank_mask:0xf
	v_mov_b32_dpp v72, v42 quad_perm:[1,0,3,2] row_mask:0xf bank_mask:0xf
	v_mov_b32_dpp v73, v58 quad_perm:[1,0,3,2] row_mask:0xf bank_mask:0xf
	v_cvt_pk_bf16_f32 v10, v10, v70
	v_cvt_pk_bf16_f32 v26, v26, v71
	v_cvt_pk_bf16_f32 v42, v42, v72
	v_cvt_pk_bf16_f32 v58, v58, v73
	ds_read_u16 v74, v78 offset:20736
	ds_read_u16 v75, v78 offset:20800
	ds_read_u16 v76, v78 offset:20864
	ds_read_u16 v77, v78 offset:20928
	s_waitcnt lgkmcnt(0)
	v_lshlrev_b32_e32 v74, 16, v74
	v_lshlrev_b32_e32 v75, 16, v75
	v_lshlrev_b32_e32 v76, 16, v76
	v_lshlrev_b32_e32 v77, 16, v77
	v_mul_f32_e32 v74, v67, v74
	v_mul_f32_e32 v75, v67, v75
	v_mul_f32_e32 v76, v67, v76
	v_mul_f32_e32 v77, v67, v77
	v_mul_f32_e32 v11, v11, v74
	v_mul_f32_e32 v27, v27, v75
	v_mul_f32_e32 v43, v43, v76
	v_mul_f32_e32 v59, v59, v77
	s_nop 0
	v_mov_b32_dpp v70, v11 quad_perm:[1,0,3,2] row_mask:0xf bank_mask:0xf
	v_mov_b32_dpp v71, v27 quad_perm:[1,0,3,2] row_mask:0xf bank_mask:0xf
	v_mov_b32_dpp v72, v43 quad_perm:[1,0,3,2] row_mask:0xf bank_mask:0xf
	v_mov_b32_dpp v73, v59 quad_perm:[1,0,3,2] row_mask:0xf bank_mask:0xf
	v_cvt_pk_bf16_f32 v11, v11, v70
	v_cvt_pk_bf16_f32 v27, v27, v71
	v_cvt_pk_bf16_f32 v43, v43, v72
	v_cvt_pk_bf16_f32 v59, v59, v73
	ds_read_u16 v74, v78 offset:20992
	ds_read_u16 v75, v78 offset:21056
	ds_read_u16 v76, v78 offset:21120
	ds_read_u16 v77, v78 offset:21184
	s_waitcnt lgkmcnt(0)
	v_lshlrev_b32_e32 v74, 16, v74
	v_lshlrev_b32_e32 v75, 16, v75
	v_lshlrev_b32_e32 v76, 16, v76
	v_lshlrev_b32_e32 v77, 16, v77
	v_mul_f32_e32 v74, v68, v74
	v_mul_f32_e32 v75, v68, v75
	v_mul_f32_e32 v76, v68, v76
	v_mul_f32_e32 v77, v68, v77
	v_mul_f32_e32 v12, v12, v74
	v_mul_f32_e32 v28, v28, v75
	v_mul_f32_e32 v44, v44, v76
	v_mul_f32_e32 v60, v60, v77
	s_nop 0
	v_mov_b32_dpp v70, v12 quad_perm:[1,0,3,2] row_mask:0xf bank_mask:0xf
	v_mov_b32_dpp v71, v28 quad_perm:[1,0,3,2] row_mask:0xf bank_mask:0xf
	v_mov_b32_dpp v72, v44 quad_perm:[1,0,3,2] row_mask:0xf bank_mask:0xf
	v_mov_b32_dpp v73, v60 quad_perm:[1,0,3,2] row_mask:0xf bank_mask:0xf
	v_cvt_pk_bf16_f32 v12, v12, v70
	v_cvt_pk_bf16_f32 v28, v28, v71
	v_cvt_pk_bf16_f32 v44, v44, v72
	v_cvt_pk_bf16_f32 v60, v60, v73
	ds_read_u16 v74, v78 offset:21248
	ds_read_u16 v75, v78 offset:21312
	ds_read_u16 v76, v78 offset:21376
	ds_read_u16 v77, v78 offset:21440
	s_waitcnt lgkmcnt(0)
; #define LAS __attribute__((address_space(3)))
; __device__ __forceinline__ float bf2f(unsigned h) { return __uint_as_float(h << 16); }
; __device__ __forceinline__ unsigned cvt_pk_bf16(float lo, float hi) { unsigned r; asm volatile("v_cvt_pk_bf16_f32 %0, %1, %2" : "=v"(r) : "v"(lo), "v"(hi)); return r; }
; __device__ __forceinline__ int crow(int r, int hi) { return (r & 3) + 8 * (r >> 2) + 4 * hi; }
; __device__ __forceinline__ void retout_phase(const bf16_t* RQ, const bf16_t* RK, const bf16_t* RV, const bf16_t* RG, const bf16_t* ST, bf16_t* Y, lptr lds, int blk, int G, int tid_) {
;     ...
;         const LAS bf16_t* gp = (const LAS bf16_t*)(lds + ci * 32768 + 16384 + (32 * tb) * 256) + r32; bf16_t* yp = Y + ((size_t)(b * SEQ + n * 64 + 32 * tb)) * DM + 1024 + hr * HD + r32;
; #pragma unroll
;         for (int r = 0; r < 16; ++r) { const int tr = crow(r, hi);
;             float v0 = o[0][r], v1 = o[1][r], v2 = o[2][r], v3 = o[3][r];
;             float ss = (v0 * v0 + v1 * v1) + (v2 * v2 + v3 * v3);
;             ss += __shfl_xor(ss, 1); ss += __shfl_xor(ss, 2); ss += __shfl_xor(ss, 4); ss += __shfl_xor(ss, 8); ss += __shfl_xor(ss, 16);
;             const float rs = rsqrtf(ss * (1.0f / 128.0f) + EPS);
;             v0 *= rs * bf2f(gp[tr * HD]); v1 *= rs * bf2f(gp[tr * HD + 32]); v2 *= rs * bf2f(gp[tr * HD + 64]); v3 *= rs * bf2f(gp[tr * HD + 96]);
;             const float n0 = __shfl_xor(v0, 1), n1 = __shfl_xor(v1, 1), n2 = __shfl_xor(v2, 1), n3 = __shfl_xor(v3, 1);
;             if ((r32 & 1) == 0) { bf16_t* op = yp + (size_t)tr * DM;
;                 *(unsigned*)(op) = cvt_pk_bf16(v0, n0); *(unsigned*)(op + 32) = cvt_pk_bf16(v1, n1); *(unsigned*)(op + 64) = cvt_pk_bf16(v2, n2); *(unsigned*)(op + 96) = cvt_pk_bf16(v3, n3); } }
	v_lshlrev_b32_e32 v74, 16, v74
	v_lshlrev_b32_e32 v75, 16, v75
	v_lshlrev_b32_e32 v76, 16, v76
	v_lshlrev_b32_e32 v77, 16, v77
	v_mul_f32_e32 v74, v69, v74
	v_mul_f32_e32 v75, v69, v75
	v_mul_f32_e32 v76, v69, v76
	v_mul_f32_e32 v77, v69, v77
	v_mul_f32_e32 v13, v13, v74
	v_mul_f32_e32 v29, v29, v75
	v_mul_f32_e32 v45, v45, v76
	v_mul_f32_e32 v61, v61, v77
	s_nop 0
	v_mov_b32_dpp v70, v13 quad_perm:[1,0,3,2] row_mask:0xf bank_mask:0xf
	v_mov_b32_dpp v71, v29 quad_perm:[1,0,3,2] row_mask:0xf bank_mask:0xf
	v_mov_b32_dpp v72, v45 quad_perm:[1,0,3,2] row_mask:0xf bank_mask:0xf
	v_mov_b32_dpp v73, v61 quad_perm:[1,0,3,2] row_mask:0xf bank_mask:0xf
	v_cvt_pk_bf16_f32 v13, v13, v70
	v_cvt_pk_bf16_f32 v29, v29, v71
	v_cvt_pk_bf16_f32 v45, v45, v72
	v_cvt_pk_bf16_f32 v61, v61, v73
	v_pk_mul_f32 v[66:67], v[14:15], v[14:15]
	v_pk_mul_f32 v[68:69], v[16:17], v[16:17]
	v_pk_fma_f32 v[66:67], v[30:31], v[30:31], v[66:67]
	v_pk_fma_f32 v[68:69], v[32:33], v[32:33], v[68:69]
	v_pk_fma_f32 v[66:67], v[46:47], v[46:47], v[66:67]
	v_pk_fma_f32 v[68:69], v[48:49], v[48:49], v[68:69]
	v_pk_fma_f32 v[66:67], v[62:63], v[62:63], v[66:67]
	v_pk_fma_f32 v[68:69], v[64:65], v[64:65], v[68:69]
	s_nop 1
	v_add_f32_dpp v66, v66, v66 quad_perm:[1,0,3,2] row_mask:0xf bank_mask:0xf
	v_add_f32_dpp v67, v67, v67 quad_perm:[1,0,3,2] row_mask:0xf bank_mask:0xf
	v_add_f32_dpp v68, v68, v68 quad_perm:[1,0,3,2] row_mask:0xf bank_mask:0xf
	v_add_f32_dpp v69, v69, v69 quad_perm:[1,0,3,2] row_mask:0xf bank_mask:0xf
	v_add_f32_dpp v66, v66, v66 quad_perm:[2,3,0,1] row_mask:0xf bank_mask:0xf
	v_add_f32_dpp v67, v67, v67 quad_perm:[2,3,0,1] row_mask:0xf bank_mask:0xf
	v_add_f32_dpp v68, v68, v68 quad_perm:[2,3,0,1] row_mask:0xf bank_mask:0xf
	v_add_f32_dpp v69, v69, v69 quad_perm:[2,3,0,1] row_mask:0xf bank_mask:0xf
	v_add_f32_dpp v66, v66, v66 row_half_mirror row_mask:0xf bank_mask:0xf
	v_add_f32_dpp v67, v67, v67 row_half_mirror row_mask:0xf bank_mask:0xf
	v_add_f32_dpp v68, v68, v68 row_half_mirror row_mask:0xf bank_mask:0xf
	v_add_f32_dpp v69, v69, v69 row_half_mirror row_mask:0xf bank_mask:0xf
	v_add_f32_dpp v66, v66, v66 row_mirror row_mask:0xf bank_mask:0xf
	v_add_f32_dpp v67, v67, v67 row_mirror row_mask:0xf bank_mask:0xf
	v_add_f32_dpp v68, v68, v68 row_mirror row_mask:0xf bank_mask:0xf
	v_add_f32_dpp v69, v69, v69 row_mirror row_mask:0xf bank_mask:0xf
	v_mov_b32_e32 v70, v66
	v_mov_b32_e32 v71, v67
	v_mov_b32_e32 v72, v68
	v_mov_b32_e32 v73, v69
	v_permlane16_swap_b32_e32 v66, v70
	v_permlane16_swap_b32_e32 v67, v71
	v_permlane16_swap_b32_e32 v68, v72
	v_permlane16_swap_b32_e32 v69, v73
	v_add_f32_e32 v66, v66, v70
	v_add_f32_e32 v67, v67, v71
	v_add_f32_e32 v68, v68, v72
	v_add_f32_e32 v69, v69, v73
	v_fmamk_f32 v66, v66, 0x3c000000, v192
	v_fmamk_f32 v67, v67, 0x3c000000, v192
	v_fmamk_f32 v68, v68, 0x3c000000, v192
	v_fmamk_f32 v69, v69, 0x3c000000, v192
	v_rsq_f32_e32 v66, v66
	v_rsq_f32_e32 v67, v67
	v_rsq_f32_e32 v68, v68
	v_rsq_f32_e32 v69, v69
	ds_read_u16 v74, v78 offset:22528
	ds_read_u16 v75, v78 offset:22592
	ds_read_u16 v76, v78 offset:22656
	ds_read_u16 v77, v78 offset:22720
	s_waitcnt lgkmcnt(0)
	v_lshlrev_b32_e32 v74, 16, v74
	v_lshlrev_b32_e32 v75, 16, v75
	v_lshlrev_b32_e32 v76, 16, v76
	v_lshlrev_b32_e32 v77, 16, v77
	v_mul_f32_e32 v74, v66, v74
	v_mul_f32_e32 v75, v66, v75
	v_mul_f32_e32 v76, v66, v76
	v_mul_f32_e32 v77, v66, v77
	v_mul_f32_e32 v14, v14, v74
	v_mul_f32_e32 v30, v30, v75
	v_mul_f32_e32 v46, v46, v76
	v_mul_f32_e32 v62, v62, v77
	s_nop 0
	v_mov_b32_dpp v70, v14 quad_perm:[1,0,3,2] row_mask:0xf bank_mask:0xf
	v_mov_b32_dpp v71, v30 quad_perm:[1,0,3,2] row_mask:0xf bank_mask:0xf
	v_mov_b32_dpp v72, v46 quad_perm:[1,0,3,2] row_mask:0xf bank_mask:0xf
	v_mov_b32_dpp v73, v62 quad_perm:[1,0,3,2] row_mask:0xf bank_mask:0xf
	v_cvt_pk_bf16_f32 v14, v14, v70
	v_cvt_pk_bf16_f32 v30, v30, v71
	v_cvt_pk_bf16_f32 v46, v46, v72
	v_cvt_pk_bf16_f32 v62, v62, v73
	ds_read_u16 v74, v78 offset:22784
	ds_read_u16 v75, v78 offset:22848
	ds_read_u16 v76, v78 offset:22912
	ds_read_u16 v77, v78 offset:22976
	s_waitcnt lgkmcnt(0)
	v_lshlrev_b32_e32 v74, 16, v74
	v_lshlrev_b32_e32 v75, 16, v75
	v_lshlrev_b32_e32 v76, 16, v76
	v_lshlrev_b32_e32 v77, 16, v77
	v_mul_f32_e32 v74, v67, v74
	v_mul_f32_e32 v75, v67, v75
	v_mul_f32_e32 v76, v67, v76
	v_mul_f32_e32 v77, v67, v77
	v_mul_f32_e32 v15, v15, v74
	v_mul_f32_e32 v31, v31, v75
	v_mul_f32_e32 v47, v47, v76
	v_mul_f32_e32 v63, v63, v77
	s_nop 0
	v_mov_b32_dpp v70, v15 quad_perm:[1,0,3,2] row_mask:0xf bank_mask:0xf
	v_mov_b32_dpp v71, v31 quad_perm:[1,0,3,2] row_mask:0xf bank_mask:0xf
	v_mov_b32_dpp v72, v47 quad_perm:[1,0,3,2] row_mask:0xf bank_mask:0xf
	v_mov_b32_dpp v73, v63 quad_perm:[1,0,3,2] row_mask:0xf bank_mask:0xf
	v_cvt_pk_bf16_f32 v15, v15, v70
	v_cvt_pk_bf16_f32 v31, v31, v71
	v_cvt_pk_bf16_f32 v47, v47, v72
	v_cvt_pk_bf16_f32 v63, v63, v73
	ds_read_u16 v74, v78 offset:23040
	ds_read_u16 v75, v78 offset:23104
	ds_read_u16 v76, v78 offset:23168
	ds_read_u16 v77, v78 offset:23232
	s_waitcnt lgkmcnt(0)
; __device__ __forceinline__ unsigned cvt_pk_bf16(float lo, float hi) { unsigned r; asm volatile("v_cvt_pk_bf16_f32 %0, %1, %2" : "=v"(r) : "v"(lo), "v"(hi)); return r; }
; __device__ __forceinline__ void retout_phase(const bf16_t* RQ, const bf16_t* RK, const bf16_t* RV, const bf16_t* RG, const bf16_t* ST, bf16_t* Y, lptr lds, int blk, int G, int tid_) {
;     ...
;             if ((r32 & 1) == 0) { bf16_t* op = yp + (size_t)tr * DM;
;                 *(unsigned*)(op) = cvt_pk_bf16(v0, n0); *(unsigned*)(op + 32) = cvt_pk_bf16(v1, n1); *(unsigned*)(op + 64) = cvt_pk_bf16(v2, n2); *(unsigned*)(op + 96) = cvt_pk_bf16(v3, n3); } }
	v_lshlrev_b32_e32 v74, 16, v74
	v_lshlrev_b32_e32 v75, 16, v75
	v_lshlrev_b32_e32 v76, 16, v76
	v_lshlrev_b32_e32 v77, 16, v77
	v_mul_f32_e32 v74, v68, v74
	v_mul_f32_e32 v75, v68, v75
	v_mul_f32_e32 v76, v68, v76
	v_mul_f32_e32 v77, v68, v77
	v_mul_f32_e32 v16, v16, v74
	v_mul_f32_e32 v32, v32, v75
	v_mul_f32_e32 v48, v48, v76
	v_mul_f32_e32 v64, v64, v77
	s_nop 0
	v_mov_b32_dpp v70, v16 quad_perm:[1,0,3,2] row_mask:0xf bank_mask:0xf
	v_mov_b32_dpp v71, v32 quad_perm:[1,0,3,2] row_mask:0xf bank_mask:0xf
	v_mov_b32_dpp v72, v48 quad_perm:[1,0,3,2] row_mask:0xf bank_mask:0xf
	v_mov_b32_dpp v73, v64 quad_perm:[1,0,3,2] row_mask:0xf bank_mask:0xf
	v_cvt_pk_bf16_f32 v16, v16, v70
	v_cvt_pk_bf16_f32 v32, v32, v71
	v_cvt_pk_bf16_f32 v48, v48, v72
	v_cvt_pk_bf16_f32 v64, v64, v73
	ds_read_u16 v74, v78 offset:23296
	ds_read_u16 v75, v78 offset:23360
	ds_read_u16 v76, v78 offset:23424
	ds_read_u16 v77, v78 offset:23488
	s_waitcnt lgkmcnt(0)
	v_lshlrev_b32_e32 v74, 16, v74
	v_lshlrev_b32_e32 v75, 16, v75
	v_lshlrev_b32_e32 v76, 16, v76
	v_lshlrev_b32_e32 v77, 16, v77
	v_mul_f32_e32 v74, v69, v74
	v_mul_f32_e32 v75, v69, v75
	v_mul_f32_e32 v76, v69, v76
	v_mul_f32_e32 v77, v69, v77
	v_mul_f32_e32 v17, v17, v74
	v_mul_f32_e32 v33, v33, v75
	v_mul_f32_e32 v49, v49, v76
	v_mul_f32_e32 v65, v65, v77
	s_nop 0
	v_mov_b32_dpp v70, v17 quad_perm:[1,0,3,2] row_mask:0xf bank_mask:0xf
	v_mov_b32_dpp v71, v33 quad_perm:[1,0,3,2] row_mask:0xf bank_mask:0xf
	v_mov_b32_dpp v72, v49 quad_perm:[1,0,3,2] row_mask:0xf bank_mask:0xf
	v_mov_b32_dpp v73, v65 quad_perm:[1,0,3,2] row_mask:0xf bank_mask:0xf
	v_cvt_pk_bf16_f32 v17, v17, v70
	v_cvt_pk_bf16_f32 v33, v33, v71
	v_cvt_pk_bf16_f32 v49, v49, v72
	v_cvt_pk_bf16_f32 v65, v65, v73
	s_mov_b64 exec, vcc
	global_store_dword v162, v2, s[4:5]
	global_store_dword v162, v18, s[4:5] offset:64
	global_store_dword v162, v34, s[4:5] offset:128
	global_store_dword v162, v50, s[4:5] offset:192
	s_add_u32 s4, s4, 0x1000
	s_addc_u32 s5, s5, 0
	global_store_dword v162, v3, s[4:5]
	global_store_dword v162, v19, s[4:5] offset:64
	global_store_dword v162, v35, s[4:5] offset:128
	global_store_dword v162, v51, s[4:5] offset:192
	s_add_u32 s4, s4, 0x1000
	s_addc_u32 s5, s5, 0
	global_store_dword v162, v4, s[4:5]
	global_store_dword v162, v20, s[4:5] offset:64
	global_store_dword v162, v36, s[4:5] offset:128
	global_store_dword v162, v52, s[4:5] offset:192
	s_add_u32 s4, s4, 0x1000
	s_addc_u32 s5, s5, 0
	global_store_dword v162, v5, s[4:5]
	global_store_dword v162, v21, s[4:5] offset:64
	global_store_dword v162, v37, s[4:5] offset:128
	global_store_dword v162, v53, s[4:5] offset:192
	s_add_u32 s4, s4, 0x5000
	s_addc_u32 s5, s5, 0
	global_store_dword v162, v6, s[4:5]
	global_store_dword v162, v22, s[4:5] offset:64
	global_store_dword v162, v38, s[4:5] offset:128
	global_store_dword v162, v54, s[4:5] offset:192
	s_add_u32 s4, s4, 0x1000
	s_addc_u32 s5, s5, 0
	global_store_dword v162, v7, s[4:5]
	global_store_dword v162, v23, s[4:5] offset:64
	global_store_dword v162, v39, s[4:5] offset:128
	global_store_dword v162, v55, s[4:5] offset:192
	s_add_u32 s4, s4, 0x1000
	s_addc_u32 s5, s5, 0
	global_store_dword v162, v8, s[4:5]
	global_store_dword v162, v24, s[4:5] offset:64
	global_store_dword v162, v40, s[4:5] offset:128
	global_store_dword v162, v56, s[4:5] offset:192
	s_add_u32 s4, s4, 0x1000
	s_addc_u32 s5, s5, 0
	global_store_dword v162, v9, s[4:5]
	global_store_dword v162, v25, s[4:5] offset:64
	global_store_dword v162, v41, s[4:5] offset:128
	global_store_dword v162, v57, s[4:5] offset:192
	s_add_u32 s4, s4, 0x5000
	s_addc_u32 s5, s5, 0
	global_store_dword v162, v10, s[4:5]
	global_store_dword v162, v26, s[4:5] offset:64
	global_store_dword v162, v42, s[4:5] offset:128
	global_store_dword v162, v58, s[4:5] offset:192
	s_add_u32 s4, s4, 0x1000
	s_addc_u32 s5, s5, 0
	global_store_dword v162, v11, s[4:5]
	global_store_dword v162, v27, s[4:5] offset:64
	global_store_dword v162, v43, s[4:5] offset:128
	global_store_dword v162, v59, s[4:5] offset:192
	s_add_u32 s4, s4, 0x1000
	s_addc_u32 s5, s5, 0
	global_store_dword v162, v12, s[4:5]
	global_store_dword v162, v28, s[4:5] offset:64
	global_store_dword v162, v44, s[4:5] offset:128
	global_store_dword v162, v60, s[4:5] offset:192
	s_add_u32 s4, s4, 0x1000
	s_addc_u32 s5, s5, 0
	global_store_dword v162, v13, s[4:5]
	global_store_dword v162, v29, s[4:5] offset:64
	global_store_dword v162, v45, s[4:5] offset:128
	global_store_dword v162, v61, s[4:5] offset:192
	s_add_u32 s4, s4, 0x5000
	s_addc_u32 s5, s5, 0
	global_store_dword v162, v14, s[4:5]
	global_store_dword v162, v30, s[4:5] offset:64
	global_store_dword v162, v46, s[4:5] offset:128
	global_store_dword v162, v62, s[4:5] offset:192
	s_add_u32 s4, s4, 0x1000
	s_addc_u32 s5, s5, 0
	global_store_dword v162, v15, s[4:5]
	global_store_dword v162, v31, s[4:5] offset:64
	global_store_dword v162, v47, s[4:5] offset:128
	global_store_dword v162, v63, s[4:5] offset:192
	s_add_u32 s4, s4, 0x1000
	s_addc_u32 s5, s5, 0
	global_store_dword v162, v16, s[4:5]
	global_store_dword v162, v32, s[4:5] offset:64
	global_store_dword v162, v48, s[4:5] offset:128
	global_store_dword v162, v64, s[4:5] offset:192
	s_add_u32 s4, s4, 0x1000
	s_addc_u32 s5, s5, 0
	global_store_dword v162, v17, s[4:5]
	global_store_dword v162, v33, s[4:5] offset:64
	global_store_dword v162, v49, s[4:5] offset:128
	global_store_dword v162, v65, s[4:5] offset:192
	s_mov_b64 exec, -1
	s_mov_b64 s[4:5], -1
	s_branch .LBB0_777
